# plus: first K-iteration of in-proj and FFN-up units peeled with zero SrcC, accumulator zeroing moves removed
# speedup vs baseline: 1.0102x; 1.0032x over previous
;     __host__ __device__ bool next(int i, Unit& u) const { const long L = (long)i * G + c; if (L >= maxL) return false; return unit_of(L, u); }
;     __device__ __forceinline__ const char* a_base(const Gemm& g, const Unit& u, size_t tstep) const { return (const char*)g.A + (size_t)u.pm * tstep; }
;     __device__ __forceinline__ const char* b_base(const Gemm& g, const Unit& u, size_t tstep) const { return (const char*)g.Bt + (size_t)u.pn * tstep; }
; #define PG8_STAGE(bufoff, gbase, voff) do { _Pragma("unroll") for (int _i = 0; _i < 2; ++_i) \
;         __builtin_amdgcn_global_load_lds((const unsigned*)((const char*)(gbase) + (voff)[_i]), (PG8_LAS unsigned*)(lds + (bufoff) + ldsw + _i * 8192), 16, 0, 0); } while (0)
; #define PG8_WAIT_V(n) asm volatile("s_waitcnt vmcnt(" #n ")" ::: "memory")
; #define PG8_WAIT_L(n) asm volatile("s_waitcnt lgkmcnt(" #n ")" ::: "memory")
; template <class Epi, class Sched, bool ALIGN_EPI = false, bool SP2 = false>
; __device__ __forceinline__ void gemm_phase(PG8_LAS unsigned char* lds, const Gemm g, const Sched& S, const Epi& E, const int wave_id_in) {
;     ...
;         const bool has_next = S.next(ui + 1, nxt);
;         const char* nA = has_next ? S.a_base(g, nxt, tstep) : cA; const char* nB = has_next ? S.b_base(g, nxt, tstep) : cB;
;         for (int t = 0; t < nt; t += 2) {
;             const bool last = (t == nt - 2);
;             const char* a1 = cA + (size_t)(t + 1) * kstep;
;             const char* a2 = last ? nA : cA + (size_t)(t + 2) * kstep; const char* b2 = last ? nB : cB + (size_t)(t + 2) * kstep;
;             const char* a3 = a2 + kstep; const char* b3 = b2 + kstep;
;             if (last && has_next) S.a_ready(nxt);
;             if constexpr (SP2) {
;             PG8_LDB(B0, 0, 0); PG8_LDB(B1, 0, 1); PG8_SCHED; PG8_LDA(At, 0, 0); PG8_STAGE(PG8_SA(1, 1), a1 + hstep, voffA);
;             PG8_WAIT_V(8); PG8_WAIT_L(0); PG8_BAR; __builtin_amdgcn_s_setprio(1); PG8_MMA(0, 0, At, B0); PG8_MMA(0, 1, At, B1); __builtin_amdgcn_s_setprio(0); PG8_BAR; PG8_SCHED;
;             PG8_LDA(At, 0, 1); PG8_STAGE(PG8_SB(0, 0), b2, voffB); PG8_STAGE(PG8_SB(0, 1), b2 + hstep, voffB); PG8_STAGE(PG8_SA(0, 0), a2, voffA);
;             PG8_WAIT_V(8); PG8_WAIT_L(0); PG8_BAR; __builtin_amdgcn_s_setprio(1); PG8_MMA(1, 0, At, B0); PG8_MMA(1, 1, At, B1); __builtin_amdgcn_s_setprio(0); PG8_BAR; PG8_SCHED;
.LBB0_131:
	s_ashr_i32 s57, s56, 31
	s_lshl_b64 s[38:39], s[56:57], 20
	s_add_u32 s60, s47, s38
	s_addc_u32 s61, s49, s39
	s_and_b64 s[38:39], s[58:59], exec
	s_cselect_b32 s25, s61, s7
	s_cselect_b32 s26, s60, s6
	s_ashr_i32 s55, s54, 31
	s_lshl_b64 s[38:39], s[54:55], 20
	s_add_u32 s62, s75, s38
	s_addc_u32 s63, s78, s39
	s_and_b64 s[38:39], s[58:59], exec
	s_cselect_b32 s38, s63, s69
	s_cselect_b32 s39, s62, s68
	s_add_u32 s6, s6, 0x80080
	s_addc_u32 s7, s7, 0
	s_add_u32 s42, s68, 0x100
	s_addc_u32 s43, s69, 0
	s_mov_b32 s55, -2
	ds_read_b128 v[128:131], v221
	ds_read_b128 v[132:135], v221 offset:1024
	ds_read_b128 v[136:139], v221 offset:2048
	ds_read_b128 v[140:143], v221 offset:3072
	ds_read_b128 v[144:147], v222
	ds_read_b128 v[148:151], v222 offset:1024
	ds_read_b128 v[152:155], v222 offset:2048
	ds_read_b128 v[156:159], v222 offset:3072
	s_add_u32 s40, s6, 0xfff80080
	s_addc_u32 s41, s7, -1
	s_cmp_eq_u32 s55, 28
	s_cselect_b32 s71, s25, s41
	s_cselect_b32 s70, s26, s40
	s_cselect_b32 s69, s38, s43
	s_cselect_b32 s68, s39, s42
	v_lshl_add_u64 v[192:193], s[6:7], 0, v[206:207]
	s_add_i32 m0, s65, 0xc000
	ds_read_b128 v[160:163], v223
	ds_read_b128 v[164:167], v223 offset:1024
	ds_read_b128 v[168:171], v223 offset:2048
	ds_read_b128 v[172:175], v223 offset:3072
	ds_read_b128 v[176:179], v223 offset:4096
	ds_read_b128 v[180:183], v223 offset:5120
	ds_read_b128 v[184:187], v223 offset:6144
	ds_read_b128 v[188:191], v223 offset:7168
	global_load_lds_dwordx4 v[192:193], off
	v_lshl_add_u64 v[192:193], s[6:7], 0, v[208:209]
	s_add_i32 m0, s65, 0xe000
	s_nop 0
	global_load_lds_dwordx4 v[192:193], off
	s_waitcnt vmcnt(8)
	s_waitcnt lgkmcnt(0)
	s_barrier
	s_setprio 1
	s_waitcnt lgkmcnt(0)
	v_mfma_f32_16x16x32_bf16 v[124:127], v[128:131], v[160:163], 0
	v_mfma_f32_16x16x32_bf16 v[120:123], v[136:139], v[160:163], 0
	v_mfma_f32_16x16x32_bf16 v[108:111], v[128:131], v[168:171], 0
	v_mfma_f32_16x16x32_bf16 v[104:107], v[136:139], v[168:171], 0
	v_mfma_f32_16x16x32_bf16 v[92:95], v[128:131], v[176:179], 0
	v_mfma_f32_16x16x32_bf16 v[88:91], v[136:139], v[176:179], 0
	v_mfma_f32_16x16x32_bf16 v[76:79], v[128:131], v[184:187], 0
	v_mfma_f32_16x16x32_bf16 v[72:75], v[136:139], v[184:187], 0
	v_mfma_f32_16x16x32_bf16 v[116:119], v[144:147], v[160:163], 0
	v_mfma_f32_16x16x32_bf16 v[112:115], v[152:155], v[160:163], 0
	v_mfma_f32_16x16x32_bf16 v[100:103], v[144:147], v[168:171], 0
	v_mfma_f32_16x16x32_bf16 v[96:99], v[152:155], v[168:171], 0
	v_mfma_f32_16x16x32_bf16 v[84:87], v[144:147], v[176:179], 0
	v_mfma_f32_16x16x32_bf16 v[80:83], v[152:155], v[176:179], 0
	v_mfma_f32_16x16x32_bf16 v[68:71], v[144:147], v[184:187], 0
	v_mfma_f32_16x16x32_bf16 v[64:67], v[152:155], v[184:187], 0
	v_mfma_f32_16x16x32_bf16 v[124:127], v[132:135], v[164:167], v[124:127]
	v_mfma_f32_16x16x32_bf16 v[120:123], v[140:143], v[164:167], v[120:123]
	v_mfma_f32_16x16x32_bf16 v[108:111], v[132:135], v[172:175], v[108:111]
	v_mfma_f32_16x16x32_bf16 v[104:107], v[140:143], v[172:175], v[104:107]
	v_mfma_f32_16x16x32_bf16 v[92:95], v[132:135], v[180:183], v[92:95]
	v_mfma_f32_16x16x32_bf16 v[88:91], v[140:143], v[180:183], v[88:91]
	v_mfma_f32_16x16x32_bf16 v[76:79], v[132:135], v[188:191], v[76:79]
	v_mfma_f32_16x16x32_bf16 v[72:75], v[140:143], v[188:191], v[72:75]
	v_mfma_f32_16x16x32_bf16 v[116:119], v[148:151], v[164:167], v[116:119]
	v_mfma_f32_16x16x32_bf16 v[112:115], v[156:159], v[164:167], v[112:115]
	v_mfma_f32_16x16x32_bf16 v[100:103], v[148:151], v[172:175], v[100:103]
	v_mfma_f32_16x16x32_bf16 v[96:99], v[156:159], v[172:175], v[96:99]
	v_mfma_f32_16x16x32_bf16 v[84:87], v[148:151], v[180:183], v[84:87]
	v_mfma_f32_16x16x32_bf16 v[80:83], v[156:159], v[180:183], v[80:83]
	v_mfma_f32_16x16x32_bf16 v[68:71], v[148:151], v[188:191], v[68:71]
	v_mfma_f32_16x16x32_bf16 v[64:67], v[156:159], v[188:191], v[64:67]
	s_setprio 0
	s_barrier
	s_add_i32 s40, s93, s80
	v_lshl_add_u64 v[192:193], s[68:69], 0, v[200:201]
	s_mov_b32 m0, s40
	ds_read_b128 v[160:163], v223 offset:16384
	ds_read_b128 v[164:167], v223 offset:17408
	ds_read_b128 v[168:171], v223 offset:18432
	ds_read_b128 v[172:175], v223 offset:19456
	ds_read_b128 v[176:179], v223 offset:20480
	ds_read_b128 v[180:183], v223 offset:21504
	ds_read_b128 v[184:187], v223 offset:22528
	ds_read_b128 v[188:191], v223 offset:23552
	global_load_lds_dwordx4 v[192:193], off
	s_add_i32 m0, s40, 0x2000
	s_add_u32 s72, s68, 0x80000
	v_lshl_add_u64 v[194:195], s[68:69], 0, v[202:203]
	s_addc_u32 s73, s69, 0
	s_add_i32 s40, s94, s80
	global_load_lds_dwordx4 v[194:195], off
	v_lshl_add_u64 v[196:197], s[72:73], 0, v[200:201]
	s_mov_b32 m0, s40
	v_lshl_add_u64 v[198:199], s[70:71], 0, v[202:203]
	global_load_lds_dwordx4 v[196:197], off
	v_lshl_add_u64 v[196:197], s[72:73], 0, v[202:203]
	s_add_i32 m0, s40, 0x2000
	s_nop 0
	global_load_lds_dwordx4 v[196:197], off
	v_lshl_add_u64 v[196:197], s[70:71], 0, v[200:201]
	s_mov_b32 m0, s65
	s_nop 0
	global_load_lds_dwordx4 v[196:197], off
	s_mov_b32 m0, s67
	s_nop 0
	global_load_lds_dwordx4 v[198:199], off
	s_waitcnt vmcnt(8)
	s_waitcnt lgkmcnt(0)
	s_barrier
; #define PG8_STAGE(bufoff, gbase, voff) do { _Pragma("unroll") for (int _i = 0; _i < 2; ++_i) \
;         __builtin_amdgcn_global_load_lds((const unsigned*)((const char*)(gbase) + (voff)[_i]), (PG8_LAS unsigned*)(lds + (bufoff) + ldsw + _i * 8192), 16, 0, 0); } while (0)
; #define PG8_LDA(dst, b, h) do { _Pragma("unroll") for (int m = 0; m < 4; ++m) _Pragma("unroll") for (int k = 0; k < 2; ++k) dst[m][k] = *(const PG8_LAS bf16x8*)(lds + PG8_SA(b, h) + aoff + m * 2048 + k * 1024); } while (0)
; #define PG8_LDB(dst, b, h) do { _Pragma("unroll") for (int n = 0; n < 2; ++n) _Pragma("unroll") for (int k = 0; k < 2; ++k) dst[n][k] = *(const PG8_LAS bf16x8*)(lds + PG8_SB(b, h) + boff + n * 2048 + k * 1024); } while (0)
; #define PG8_MMA(ai, bj, At, Bt) do { _Pragma("unroll") for (int m = 0; m < 4; ++m) _Pragma("unroll") for (int n = 0; n < 2; ++n) _Pragma("unroll") for (int k = 0; k < 2; ++k) \
;         acc[ai][bj][m][n] = __builtin_amdgcn_mfma_f32_16x16x32_bf16(Bt[n][k], At[m][k], acc[ai][bj][m][n], 0, 0, 0); } while (0)
; #define PG8_WAIT_V(n) asm volatile("s_waitcnt vmcnt(" #n ")" ::: "memory")
; #define PG8_WAIT_L(n) asm volatile("s_waitcnt lgkmcnt(" #n ")" ::: "memory")
; #define PG8_BAR __builtin_amdgcn_s_barrier()
; #define PG8_SCHED __builtin_amdgcn_sched_barrier(0)
; template <class Epi, class Sched, bool ALIGN_EPI = false, bool SP2 = false>
; __device__ __forceinline__ void gemm_phase(PG8_LAS unsigned char* lds, const Gemm g, const Sched& S, const Epi& E, const int wave_id_in) {
;     ...
;             PG8_WAIT_V(8); PG8_WAIT_L(0); PG8_BAR; __builtin_amdgcn_s_setprio(1); PG8_MMA(1, 0, At, B0); PG8_MMA(1, 1, At, B1); __builtin_amdgcn_s_setprio(0); PG8_BAR; PG8_SCHED;
;             PG8_LDB(B0, 1, 0); PG8_LDB(B1, 1, 1); PG8_SCHED; PG8_LDA(At, 1, 0); PG8_STAGE(PG8_SA(0, 1), a2 + hstep, voffA);
;             PG8_WAIT_V(8); PG8_WAIT_L(0); PG8_BAR; __builtin_amdgcn_s_setprio(1); PG8_MMA(0, 0, At, B0); PG8_MMA(0, 1, At, B1); __builtin_amdgcn_s_setprio(0); PG8_BAR; PG8_SCHED;
	s_setprio 1
	s_waitcnt lgkmcnt(0)
	v_mfma_f32_16x16x32_bf16 v[60:63], v[128:131], v[160:163], 0
	v_mfma_f32_16x16x32_bf16 v[56:59], v[136:139], v[160:163], 0
	v_mfma_f32_16x16x32_bf16 v[44:47], v[128:131], v[168:171], 0
	v_mfma_f32_16x16x32_bf16 v[40:43], v[136:139], v[168:171], 0
	v_mfma_f32_16x16x32_bf16 v[28:31], v[128:131], v[176:179], 0
	v_mfma_f32_16x16x32_bf16 v[24:27], v[136:139], v[176:179], 0
	v_mfma_f32_16x16x32_bf16 v[12:15], v[128:131], v[184:187], 0
	v_mfma_f32_16x16x32_bf16 v[8:11], v[136:139], v[184:187], 0
	v_mfma_f32_16x16x32_bf16 v[52:55], v[144:147], v[160:163], 0
	v_mfma_f32_16x16x32_bf16 v[48:51], v[152:155], v[160:163], 0
	v_mfma_f32_16x16x32_bf16 v[36:39], v[144:147], v[168:171], 0
	v_mfma_f32_16x16x32_bf16 v[32:35], v[152:155], v[168:171], 0
	v_mfma_f32_16x16x32_bf16 v[20:23], v[144:147], v[176:179], 0
	v_mfma_f32_16x16x32_bf16 v[16:19], v[152:155], v[176:179], 0
	v_mfma_f32_16x16x32_bf16 v[4:7], v[144:147], v[184:187], 0
	v_mfma_f32_16x16x32_bf16 v[0:3], v[152:155], v[184:187], 0
	v_mfma_f32_16x16x32_bf16 v[60:63], v[132:135], v[164:167], v[60:63]
	v_mfma_f32_16x16x32_bf16 v[56:59], v[140:143], v[164:167], v[56:59]
	v_mfma_f32_16x16x32_bf16 v[44:47], v[132:135], v[172:175], v[44:47]
	v_mfma_f32_16x16x32_bf16 v[40:43], v[140:143], v[172:175], v[40:43]
	v_mfma_f32_16x16x32_bf16 v[28:31], v[132:135], v[180:183], v[28:31]
	v_mfma_f32_16x16x32_bf16 v[24:27], v[140:143], v[180:183], v[24:27]
	v_mfma_f32_16x16x32_bf16 v[12:15], v[132:135], v[188:191], v[12:15]
	v_mfma_f32_16x16x32_bf16 v[8:11], v[140:143], v[188:191], v[8:11]
	v_mfma_f32_16x16x32_bf16 v[52:55], v[148:151], v[164:167], v[52:55]
	v_mfma_f32_16x16x32_bf16 v[48:51], v[156:159], v[164:167], v[48:51]
	v_mfma_f32_16x16x32_bf16 v[36:39], v[148:151], v[172:175], v[36:39]
	v_mfma_f32_16x16x32_bf16 v[32:35], v[156:159], v[172:175], v[32:35]
	v_mfma_f32_16x16x32_bf16 v[20:23], v[148:151], v[180:183], v[20:23]
	v_mfma_f32_16x16x32_bf16 v[16:19], v[156:159], v[180:183], v[16:19]
	v_mfma_f32_16x16x32_bf16 v[4:7], v[148:151], v[188:191], v[4:7]
	v_mfma_f32_16x16x32_bf16 v[0:3], v[156:159], v[188:191], v[0:3]
	s_setprio 0
	s_barrier
	s_add_i32 s40, 0, 0x18000
	s_add_i32 s41, 0, 0x1c000
	v_add_u32_e32 v140, s40, v220
	v_add_u32_e32 v156, s41, v220
	ds_read_b128 v[128:131], v140
	ds_read_b128 v[132:135], v140 offset:1024
	ds_read_b128 v[136:139], v140 offset:2048
	ds_read_b128 v[140:143], v140 offset:3072
	ds_read_b128 v[144:147], v156
	ds_read_b128 v[148:151], v156 offset:1024
	ds_read_b128 v[152:155], v156 offset:2048
	ds_read_b128 v[156:159], v156 offset:3072
	s_add_u32 s70, s70, 0x80000
	s_addc_u32 s71, s71, 0
	s_mov_b32 m0, s81
	v_lshl_add_u64 v[214:215], s[70:71], 0, v[200:201]
	ds_read_b128 v[160:163], v223 offset:32768
	ds_read_b128 v[164:167], v223 offset:33792
	ds_read_b128 v[168:171], v223 offset:34816
	ds_read_b128 v[172:175], v223 offset:35840
	ds_read_b128 v[176:179], v223 offset:36864
	ds_read_b128 v[180:183], v223 offset:37888
	ds_read_b128 v[184:187], v223 offset:38912
	ds_read_b128 v[188:191], v223 offset:39936
	global_load_lds_dwordx4 v[214:215], off
	v_lshl_add_u64 v[214:215], s[70:71], 0, v[202:203]
	s_mov_b32 m0, s82
	s_nop 0
	global_load_lds_dwordx4 v[214:215], off
	s_waitcnt vmcnt(8)
	s_waitcnt lgkmcnt(0)
	s_barrier
	s_setprio 1
	s_waitcnt lgkmcnt(0)
	v_mfma_f32_16x16x32_bf16 v[124:127], v[128:131], v[160:163], v[124:127]
	v_mfma_f32_16x16x32_bf16 v[120:123], v[136:139], v[160:163], v[120:123]
	v_mfma_f32_16x16x32_bf16 v[108:111], v[128:131], v[168:171], v[108:111]
	v_mfma_f32_16x16x32_bf16 v[104:107], v[136:139], v[168:171], v[104:107]
	v_mfma_f32_16x16x32_bf16 v[92:95], v[128:131], v[176:179], v[92:95]
	v_mfma_f32_16x16x32_bf16 v[88:91], v[136:139], v[176:179], v[88:91]
	v_mfma_f32_16x16x32_bf16 v[76:79], v[128:131], v[184:187], v[76:79]
	v_mfma_f32_16x16x32_bf16 v[72:75], v[136:139], v[184:187], v[72:75]
	v_mfma_f32_16x16x32_bf16 v[116:119], v[144:147], v[160:163], v[116:119]
	v_mfma_f32_16x16x32_bf16 v[112:115], v[152:155], v[160:163], v[112:115]
	v_mfma_f32_16x16x32_bf16 v[100:103], v[144:147], v[168:171], v[100:103]
	v_mfma_f32_16x16x32_bf16 v[96:99], v[152:155], v[168:171], v[96:99]
	v_mfma_f32_16x16x32_bf16 v[84:87], v[144:147], v[176:179], v[84:87]
	v_mfma_f32_16x16x32_bf16 v[80:83], v[152:155], v[176:179], v[80:83]
	v_mfma_f32_16x16x32_bf16 v[68:71], v[144:147], v[184:187], v[68:71]
	v_mfma_f32_16x16x32_bf16 v[64:67], v[152:155], v[184:187], v[64:67]
	v_mfma_f32_16x16x32_bf16 v[124:127], v[132:135], v[164:167], v[124:127]
	v_mfma_f32_16x16x32_bf16 v[120:123], v[140:143], v[164:167], v[120:123]
	v_mfma_f32_16x16x32_bf16 v[108:111], v[132:135], v[172:175], v[108:111]
	v_mfma_f32_16x16x32_bf16 v[104:107], v[140:143], v[172:175], v[104:107]
	v_mfma_f32_16x16x32_bf16 v[92:95], v[132:135], v[180:183], v[92:95]
	v_mfma_f32_16x16x32_bf16 v[88:91], v[140:143], v[180:183], v[88:91]
	v_mfma_f32_16x16x32_bf16 v[76:79], v[132:135], v[188:191], v[76:79]
	v_mfma_f32_16x16x32_bf16 v[72:75], v[140:143], v[188:191], v[72:75]
	v_mfma_f32_16x16x32_bf16 v[116:119], v[148:151], v[164:167], v[116:119]
	v_mfma_f32_16x16x32_bf16 v[112:115], v[156:159], v[164:167], v[112:115]
	v_mfma_f32_16x16x32_bf16 v[100:103], v[148:151], v[172:175], v[100:103]
	v_mfma_f32_16x16x32_bf16 v[96:99], v[156:159], v[172:175], v[96:99]
	v_mfma_f32_16x16x32_bf16 v[84:87], v[148:151], v[180:183], v[84:87]
	v_mfma_f32_16x16x32_bf16 v[80:83], v[156:159], v[180:183], v[80:83]
	v_mfma_f32_16x16x32_bf16 v[68:71], v[148:151], v[188:191], v[68:71]
	v_mfma_f32_16x16x32_bf16 v[64:67], v[156:159], v[188:191], v[64:67]
	s_setprio 0
	s_barrier
; #define PG8_STAGE(bufoff, gbase, voff) do { _Pragma("unroll") for (int _i = 0; _i < 2; ++_i) \
;         __builtin_amdgcn_global_load_lds((const unsigned*)((const char*)(gbase) + (voff)[_i]), (PG8_LAS unsigned*)(lds + (bufoff) + ldsw + _i * 8192), 16, 0, 0); } while (0)
; #define PG8_LDA(dst, b, h) do { _Pragma("unroll") for (int m = 0; m < 4; ++m) _Pragma("unroll") for (int k = 0; k < 2; ++k) dst[m][k] = *(const PG8_LAS bf16x8*)(lds + PG8_SA(b, h) + aoff + m * 2048 + k * 1024); } while (0)
; #define PG8_MMA(ai, bj, At, Bt) do { _Pragma("unroll") for (int m = 0; m < 4; ++m) _Pragma("unroll") for (int n = 0; n < 2; ++n) _Pragma("unroll") for (int k = 0; k < 2; ++k) \
;         acc[ai][bj][m][n] = __builtin_amdgcn_mfma_f32_16x16x32_bf16(Bt[n][k], At[m][k], acc[ai][bj][m][n], 0, 0, 0); } while (0)
; #define PG8_WAIT_V(n) asm volatile("s_waitcnt vmcnt(" #n ")" ::: "memory")
; #define PG8_WAIT_L(n) asm volatile("s_waitcnt lgkmcnt(" #n ")" ::: "memory")
; #define PG8_BAR __builtin_amdgcn_s_barrier()
; #define PG8_SCHED __builtin_amdgcn_sched_barrier(0)
; template <class Epi, class Sched, bool ALIGN_EPI = false, bool SP2 = false>
; __device__ __forceinline__ void gemm_phase(PG8_LAS unsigned char* lds, const Gemm g, const Sched& S, const Epi& E, const int wave_id_in) {
;     ...
;         for (int t = 0; t < nt; t += 2) {
;     ...
;             PG8_LDA(At, 1, 1); PG8_STAGE(PG8_SB(1, 0), b3, voffB); PG8_STAGE(PG8_SB(1, 1), b3 + hstep, voffB); PG8_STAGE(PG8_SA(1, 0), a3, voffA);
;             PG8_WAIT_V(8); PG8_WAIT_L(0); PG8_BAR; __builtin_amdgcn_s_setprio(1); PG8_MMA(1, 0, At, B0); PG8_MMA(1, 1, At, B1); __builtin_amdgcn_s_setprio(0); PG8_BAR; PG8_SCHED;
	s_add_i32 s40, s40, s80
	v_lshl_add_u64 v[192:193], v[192:193], 0, s[30:31]
	s_mov_b32 m0, s40
	ds_read_b128 v[160:163], v223 offset:49152
	ds_read_b128 v[164:167], v223 offset:50176
	ds_read_b128 v[168:171], v223 offset:51200
	ds_read_b128 v[172:175], v223 offset:52224
	ds_read_b128 v[176:179], v223 offset:53248
	ds_read_b128 v[180:183], v223 offset:54272
	ds_read_b128 v[184:187], v223 offset:55296
	ds_read_b128 v[188:191], v223 offset:56320
	global_load_lds_dwordx4 v[192:193], off
	s_add_i32 m0, s40, 0x2000
	s_add_u32 s68, s68, 0x80080
	v_lshl_add_u64 v[192:193], v[194:195], 0, s[30:31]
	s_addc_u32 s69, s69, 0
	s_add_i32 s40, s41, s80
	global_load_lds_dwordx4 v[192:193], off
	v_lshl_add_u64 v[192:193], s[68:69], 0, v[200:201]
	s_mov_b32 m0, s40
	s_nop 0
	global_load_lds_dwordx4 v[192:193], off
	v_lshl_add_u64 v[192:193], s[68:69], 0, v[202:203]
	s_add_i32 m0, s40, 0x2000
	s_nop 0
	global_load_lds_dwordx4 v[192:193], off
	v_lshl_add_u64 v[192:193], v[196:197], 0, s[30:31]
	s_mov_b32 m0, s86
	s_nop 0
	global_load_lds_dwordx4 v[192:193], off
	v_lshl_add_u64 v[192:193], v[198:199], 0, s[30:31]
	s_mov_b32 m0, s87
	s_nop 0
	global_load_lds_dwordx4 v[192:193], off
	s_waitcnt vmcnt(8)
	s_waitcnt lgkmcnt(0)
	s_barrier
	s_setprio 1
	s_waitcnt lgkmcnt(0)
	v_mfma_f32_16x16x32_bf16 v[60:63], v[128:131], v[160:163], v[60:63]
	v_mfma_f32_16x16x32_bf16 v[56:59], v[136:139], v[160:163], v[56:59]
	v_mfma_f32_16x16x32_bf16 v[44:47], v[128:131], v[168:171], v[44:47]
	v_mfma_f32_16x16x32_bf16 v[40:43], v[136:139], v[168:171], v[40:43]
	v_mfma_f32_16x16x32_bf16 v[28:31], v[128:131], v[176:179], v[28:31]
	v_mfma_f32_16x16x32_bf16 v[24:27], v[136:139], v[176:179], v[24:27]
	v_mfma_f32_16x16x32_bf16 v[12:15], v[128:131], v[184:187], v[12:15]
	v_mfma_f32_16x16x32_bf16 v[8:11], v[136:139], v[184:187], v[8:11]
	v_mfma_f32_16x16x32_bf16 v[52:55], v[144:147], v[160:163], v[52:55]
	v_mfma_f32_16x16x32_bf16 v[48:51], v[152:155], v[160:163], v[48:51]
	v_mfma_f32_16x16x32_bf16 v[36:39], v[144:147], v[168:171], v[36:39]
	v_mfma_f32_16x16x32_bf16 v[32:35], v[152:155], v[168:171], v[32:35]
	v_mfma_f32_16x16x32_bf16 v[20:23], v[144:147], v[176:179], v[20:23]
	v_mfma_f32_16x16x32_bf16 v[16:19], v[152:155], v[176:179], v[16:19]
	v_mfma_f32_16x16x32_bf16 v[4:7], v[144:147], v[184:187], v[4:7]
	v_mfma_f32_16x16x32_bf16 v[0:3], v[152:155], v[184:187], v[0:3]
	v_mfma_f32_16x16x32_bf16 v[60:63], v[132:135], v[164:167], v[60:63]
	v_mfma_f32_16x16x32_bf16 v[56:59], v[140:143], v[164:167], v[56:59]
	v_mfma_f32_16x16x32_bf16 v[44:47], v[132:135], v[172:175], v[44:47]
	v_mfma_f32_16x16x32_bf16 v[40:43], v[140:143], v[172:175], v[40:43]
	v_mfma_f32_16x16x32_bf16 v[28:31], v[132:135], v[180:183], v[28:31]
	v_mfma_f32_16x16x32_bf16 v[24:27], v[140:143], v[180:183], v[24:27]
	v_mfma_f32_16x16x32_bf16 v[12:15], v[132:135], v[188:191], v[12:15]
	v_mfma_f32_16x16x32_bf16 v[8:11], v[140:143], v[188:191], v[8:11]
	v_mfma_f32_16x16x32_bf16 v[52:55], v[148:151], v[164:167], v[52:55]
	v_mfma_f32_16x16x32_bf16 v[48:51], v[156:159], v[164:167], v[48:51]
	v_mfma_f32_16x16x32_bf16 v[36:39], v[148:151], v[172:175], v[36:39]
	v_mfma_f32_16x16x32_bf16 v[32:35], v[156:159], v[172:175], v[32:35]
	v_mfma_f32_16x16x32_bf16 v[20:23], v[148:151], v[180:183], v[20:23]
	v_mfma_f32_16x16x32_bf16 v[16:19], v[156:159], v[180:183], v[16:19]
	v_mfma_f32_16x16x32_bf16 v[4:7], v[148:151], v[188:191], v[4:7]
	v_mfma_f32_16x16x32_bf16 v[0:3], v[156:159], v[188:191], v[0:3]
	s_setprio 0
	s_barrier
	s_add_i32 s55, s55, 2
	s_add_u32 s6, s6, 0x100
	s_addc_u32 s7, s7, 0
	s_add_u32 s42, s42, 0x100
	s_addc_u32 s43, s43, 0
	s_cmp_gt_u32 s55, 29
	s_cbranch_scc0 .LBB0_132
	s_branch .Lpeel_exit_inproj

; #define PG8_BAR __builtin_amdgcn_s_barrier()
; template <class Epi, class Sched, bool ALIGN_EPI = false, bool SP2 = false>
; __device__ __forceinline__ void gemm_phase(PG8_LAS unsigned char* lds, const Gemm g, const Sched& S, const Epi& E, const int wave_id_in) {
;     ...
;         if constexpr (ALIGN_EPI) { if (wr == 0) PG8_BAR; }
.Lpeel_exit_inproj:
	s_and_b64 vcc, exec, s[34:35]
	s_cbranch_vccz .LBB0_135
	s_barrier

;     __host__ __device__ bool next(int i, Unit& u) const { const long L = (long)i * G + c; if (L >= maxL) return false; return unit_of(L, u); }
;     __device__ __forceinline__ const char* a_base(const Gemm& g, const Unit& u, size_t tstep) const { return (const char*)g.A + (size_t)u.pm * tstep; }
;     __device__ __forceinline__ const char* b_base(const Gemm& g, const Unit& u, size_t tstep) const { return (const char*)g.Bt + (size_t)u.pn * tstep; }
; #define PG8_STAGE(bufoff, gbase, voff) do { _Pragma("unroll") for (int _i = 0; _i < 2; ++_i) \
;         __builtin_amdgcn_global_load_lds((const unsigned*)((const char*)(gbase) + (voff)[_i]), (PG8_LAS unsigned*)(lds + (bufoff) + ldsw + _i * 8192), 16, 0, 0); } while (0)
; #define PG8_WAIT_V(n) asm volatile("s_waitcnt vmcnt(" #n ")" ::: "memory")
; #define PG8_WAIT_L(n) asm volatile("s_waitcnt lgkmcnt(" #n ")" ::: "memory")
; template <class Epi, class Sched, bool ALIGN_EPI = false, bool SP2 = false>
; __device__ __forceinline__ void gemm_phase(PG8_LAS unsigned char* lds, const Gemm g, const Sched& S, const Epi& E, const int wave_id_in) {
;     ...
;         const bool has_next = S.next(ui + 1, nxt);
;         const char* nA = has_next ? S.a_base(g, nxt, tstep) : cA; const char* nB = has_next ? S.b_base(g, nxt, tstep) : cB;
;         for (int t = 0; t < nt; t += 2) {
;             const bool last = (t == nt - 2);
;             const char* a1 = cA + (size_t)(t + 1) * kstep;
;             const char* a2 = last ? nA : cA + (size_t)(t + 2) * kstep; const char* b2 = last ? nB : cB + (size_t)(t + 2) * kstep;
;             const char* a3 = a2 + kstep; const char* b3 = b2 + kstep;
;             if (last && has_next) S.a_ready(nxt);
;             if constexpr (SP2) {
;             PG8_LDB(B0, 0, 0); PG8_LDB(B1, 0, 1); PG8_SCHED; PG8_LDA(At, 0, 0); PG8_STAGE(PG8_SA(1, 1), a1 + hstep, voffA);
;             PG8_WAIT_V(8); PG8_WAIT_L(0); PG8_BAR; __builtin_amdgcn_s_setprio(1); PG8_MMA(0, 0, At, B0); PG8_MMA(0, 1, At, B1); __builtin_amdgcn_s_setprio(0); PG8_BAR; PG8_SCHED;
;             PG8_LDA(At, 0, 1); PG8_STAGE(PG8_SB(0, 0), b2, voffB); PG8_STAGE(PG8_SB(0, 1), b2 + hstep, voffB); PG8_STAGE(PG8_SA(0, 0), a2, voffA);
;             PG8_WAIT_V(8); PG8_WAIT_L(0); PG8_BAR; __builtin_amdgcn_s_setprio(1); PG8_MMA(1, 0, At, B0); PG8_MMA(1, 1, At, B1); __builtin_amdgcn_s_setprio(0); PG8_BAR; PG8_SCHED;
.LBB0_818:
	s_ashr_i32 s67, s66, 31
	s_lshl_b64 s[68:69], s[66:67], 20
	s_add_u32 s68, s78, s68
	s_addc_u32 s69, s79, s69
	s_and_b64 s[70:71], s[6:7], exec
	s_cselect_b32 s9, s69, s11
	s_cselect_b32 s27, s68, s10
	s_ashr_i32 s65, s64, 31
	s_lshl_b64 s[70:71], s[64:65], 20
	s_add_u32 s70, s44, s70
	s_addc_u32 s71, s45, s71
	s_and_b64 s[72:73], s[6:7], exec
	s_cselect_b32 s65, s71, s13
	s_cselect_b32 s74, s70, s12
	s_add_u32 s10, s10, 0x80080
	s_addc_u32 s11, s11, 0
	s_add_u32 s75, s12, 0x100
	s_addc_u32 vcc_lo, s13, 0
	s_mov_b32 vcc_hi, -2
	s_waitcnt lgkmcnt(0)
	ds_read_b128 v[44:47], v221
	ds_read_b128 v[48:51], v221 offset:1024
	ds_read_b128 v[56:59], v221 offset:2048
	s_waitcnt lgkmcnt(0)
	ds_read_b128 v[60:63], v221 offset:3072
	ds_read_b128 v[68:71], v222
	ds_read_b128 v[72:75], v222 offset:1024
	ds_read_b128 v[76:79], v222 offset:2048
	ds_read_b128 v[84:87], v222 offset:3072
	s_add_u32 s12, s10, 0xfff80080
	s_addc_u32 s13, s11, -1
	s_cmp_eq_u32 vcc_hi, 28
	s_cselect_b32 s73, s9, s13
	s_cselect_b32 s72, s27, s12
	s_cselect_b32 s13, s65, vcc_lo
	s_cselect_b32 s12, s74, s75
	v_lshl_add_u64 v[208:209], s[10:11], 0, v[194:195]
	s_add_i32 m0, s81, 0xc000
	ds_read_b128 v[92:95], v223
	ds_read_b128 v[96:99], v223 offset:1024
	ds_read_b128 v[120:123], v223 offset:2048
	ds_read_b128 v[124:127], v223 offset:3072
	ds_read_b128 v[168:171], v223 offset:4096
	ds_read_b128 v[180:183], v223 offset:5120
	ds_read_b128 v[200:203], v223 offset:6144
	ds_read_b128 v[204:207], v223 offset:7168
	global_load_lds_dwordx4 v[208:209], off
	v_lshl_add_u64 v[208:209], s[10:11], 0, v[196:197]
	s_add_i32 m0, s81, 0xe000
	s_nop 0
	global_load_lds_dwordx4 v[208:209], off
	s_waitcnt vmcnt(8)
	s_waitcnt lgkmcnt(0)
	s_barrier
	s_setprio 1
	s_waitcnt lgkmcnt(0)
	v_mfma_f32_16x16x32_bf16 v[40:43], v[44:47], v[92:95], 0
	v_mfma_f32_16x16x32_bf16 v[36:39], v[56:59], v[92:95], 0
	v_mfma_f32_16x16x32_bf16 v[104:107], v[68:71], v[92:95], 0
	v_mfma_f32_16x16x32_bf16 v[92:95], v[76:79], v[92:95], 0
	v_mfma_f32_16x16x32_bf16 v[108:111], v[76:79], v[120:123], 0
	v_mfma_f32_16x16x32_bf16 v[40:43], v[48:51], v[96:99], v[40:43]
	v_mfma_f32_16x16x32_bf16 v[36:39], v[60:63], v[96:99], v[36:39]
	v_mfma_f32_16x16x32_bf16 v[172:175], v[44:47], v[120:123], 0
	v_mfma_f32_16x16x32_bf16 v[164:167], v[56:59], v[120:123], 0
	v_mfma_f32_16x16x32_bf16 v[104:107], v[72:75], v[96:99], v[104:107]
	v_mfma_f32_16x16x32_bf16 v[92:95], v[84:87], v[96:99], v[92:95]
	v_mfma_f32_16x16x32_bf16 v[96:99], v[68:71], v[120:123], 0
	v_mfma_f32_16x16x32_bf16 v[120:123], v[84:87], v[124:127], v[108:111]
	v_mfma_f32_16x16x32_bf16 v[108:111], v[68:71], v[168:171], 0
	v_mfma_f32_16x16x32_bf16 v[172:175], v[48:51], v[124:127], v[172:175]
	v_mfma_f32_16x16x32_bf16 v[164:167], v[60:63], v[124:127], v[164:167]
	v_mfma_f32_16x16x32_bf16 v[96:99], v[72:75], v[124:127], v[96:99]
	v_mfma_f32_16x16x32_bf16 v[124:127], v[72:75], v[180:183], v[108:111]
	v_mfma_f32_16x16x32_bf16 v[108:111], v[76:79], v[168:171], 0
	v_mfma_f32_16x16x32_bf16 v[136:139], v[84:87], v[180:183], v[108:111]
	v_mfma_f32_16x16x32_bf16 v[108:111], v[68:71], v[200:203], 0
	v_mfma_f32_16x16x32_bf16 v[156:159], v[44:47], v[168:171], 0
	v_mfma_f32_16x16x32_bf16 v[152:155], v[56:59], v[168:171], 0
	v_mfma_f32_16x16x32_bf16 v[160:163], v[44:47], v[200:203], 0
	v_mfma_f32_16x16x32_bf16 v[132:135], v[56:59], v[200:203], 0
	v_mfma_f32_16x16x32_bf16 v[116:119], v[72:75], v[204:207], v[108:111]
	v_mfma_f32_16x16x32_bf16 v[108:111], v[76:79], v[200:203], 0
	v_mfma_f32_16x16x32_bf16 v[156:159], v[48:51], v[180:183], v[156:159]
	v_mfma_f32_16x16x32_bf16 v[152:155], v[60:63], v[180:183], v[152:155]
	v_mfma_f32_16x16x32_bf16 v[160:163], v[48:51], v[204:207], v[160:163]
	v_mfma_f32_16x16x32_bf16 v[132:135], v[60:63], v[204:207], v[132:135]
	v_mfma_f32_16x16x32_bf16 v[112:115], v[84:87], v[204:207], v[108:111]
	s_setprio 0
	s_barrier
	s_add_i32 s40, s5, s80
	v_lshl_add_u64 v[216:217], s[12:13], 0, v[186:187]
	s_mov_b32 m0, s40
	ds_read_b128 v[108:111], v223 offset:16384
	ds_read_b128 v[140:143], v223 offset:17408
	ds_read_b128 v[144:147], v223 offset:18432
	ds_read_b128 v[148:151], v223 offset:19456
	ds_read_b128 v[168:171], v223 offset:20480
	ds_read_b128 v[180:183], v223 offset:21504
	ds_read_b128 v[200:203], v223 offset:22528
	ds_read_b128 v[204:207], v223 offset:23552
	global_load_lds_dwordx4 v[216:217], off
	s_add_i32 m0, s40, 0x2000
	s_add_u32 s40, s12, 0x80000
	v_lshl_add_u64 v[218:219], s[12:13], 0, v[190:191]
	s_addc_u32 s41, s13, 0
	s_add_i32 s77, s28, s80
	global_load_lds_dwordx4 v[218:219], off
	v_lshl_add_u64 v[208:209], s[40:41], 0, v[186:187]
	s_mov_b32 m0, s77
	v_lshl_add_u64 v[226:227], s[72:73], 0, v[184:185]
	global_load_lds_dwordx4 v[208:209], off
	v_lshl_add_u64 v[208:209], s[40:41], 0, v[190:191]
	s_add_i32 m0, s77, 0x2000
	v_lshl_add_u64 v[228:229], s[72:73], 0, v[188:189]
	global_load_lds_dwordx4 v[208:209], off
	s_mov_b32 m0, s81
	s_nop 0
	global_load_lds_dwordx4 v[226:227], off
	s_mov_b32 m0, s82
	s_nop 0
	global_load_lds_dwordx4 v[228:229], off
	s_waitcnt vmcnt(8)
	s_waitcnt lgkmcnt(0)
	s_barrier
; #define PG8_STAGE(bufoff, gbase, voff) do { _Pragma("unroll") for (int _i = 0; _i < 2; ++_i) \
;         __builtin_amdgcn_global_load_lds((const unsigned*)((const char*)(gbase) + (voff)[_i]), (PG8_LAS unsigned*)(lds + (bufoff) + ldsw + _i * 8192), 16, 0, 0); } while (0)
; #define PG8_LDA(dst, b, h) do { _Pragma("unroll") for (int m = 0; m < 4; ++m) _Pragma("unroll") for (int k = 0; k < 2; ++k) dst[m][k] = *(const PG8_LAS bf16x8*)(lds + PG8_SA(b, h) + aoff + m * 2048 + k * 1024); } while (0)
; #define PG8_LDB(dst, b, h) do { _Pragma("unroll") for (int n = 0; n < 2; ++n) _Pragma("unroll") for (int k = 0; k < 2; ++k) dst[n][k] = *(const PG8_LAS bf16x8*)(lds + PG8_SB(b, h) + boff + n * 2048 + k * 1024); } while (0)
; #define PG8_MMA(ai, bj, At, Bt) do { _Pragma("unroll") for (int m = 0; m < 4; ++m) _Pragma("unroll") for (int n = 0; n < 2; ++n) _Pragma("unroll") for (int k = 0; k < 2; ++k) \
;         acc[ai][bj][m][n] = __builtin_amdgcn_mfma_f32_16x16x32_bf16(Bt[n][k], At[m][k], acc[ai][bj][m][n], 0, 0, 0); } while (0)
; #define PG8_WAIT_V(n) asm volatile("s_waitcnt vmcnt(" #n ")" ::: "memory")
; #define PG8_WAIT_L(n) asm volatile("s_waitcnt lgkmcnt(" #n ")" ::: "memory")
; #define PG8_BAR __builtin_amdgcn_s_barrier()
; #define PG8_SCHED __builtin_amdgcn_sched_barrier(0)
; template <class Epi, class Sched, bool ALIGN_EPI = false, bool SP2 = false>
; __device__ __forceinline__ void gemm_phase(PG8_LAS unsigned char* lds, const Gemm g, const Sched& S, const Epi& E, const int wave_id_in) {
;     ...
;             PG8_WAIT_V(8); PG8_WAIT_L(0); PG8_BAR; __builtin_amdgcn_s_setprio(1); PG8_MMA(1, 0, At, B0); PG8_MMA(1, 1, At, B1); __builtin_amdgcn_s_setprio(0); PG8_BAR; PG8_SCHED;
;             PG8_LDB(B0, 1, 0); PG8_LDB(B1, 1, 1); PG8_SCHED; PG8_LDA(At, 1, 0); PG8_STAGE(PG8_SA(0, 1), a2 + hstep, voffA);
;             PG8_WAIT_V(8); PG8_WAIT_L(0); PG8_BAR; __builtin_amdgcn_s_setprio(1); PG8_MMA(0, 0, At, B0); PG8_MMA(0, 1, At, B1); __builtin_amdgcn_s_setprio(0); PG8_BAR; PG8_SCHED;
	s_setprio 1
	s_waitcnt lgkmcnt(0)
	v_mfma_f32_16x16x32_bf16 v[128:131], v[44:47], v[108:111], 0
	v_mfma_f32_16x16x32_bf16 v[64:67], v[56:59], v[108:111], 0
	v_mfma_f32_16x16x32_bf16 v[100:103], v[44:47], v[144:147], 0
	v_mfma_f32_16x16x32_bf16 v[88:91], v[56:59], v[144:147], 0
	v_mfma_f32_16x16x32_bf16 v[28:31], v[44:47], v[168:171], 0
	v_mfma_f32_16x16x32_bf16 v[24:27], v[56:59], v[168:171], 0
	v_mfma_f32_16x16x32_bf16 v[44:47], v[44:47], v[200:203], 0
	v_mfma_f32_16x16x32_bf16 v[32:35], v[76:79], v[108:111], 0
	v_mfma_f32_16x16x32_bf16 v[20:23], v[68:71], v[144:147], 0
	v_mfma_f32_16x16x32_bf16 v[16:19], v[76:79], v[144:147], 0
	v_mfma_f32_16x16x32_bf16 v[12:15], v[68:71], v[168:171], 0
	v_mfma_f32_16x16x32_bf16 v[8:11], v[76:79], v[168:171], 0
	v_mfma_f32_16x16x32_bf16 v[4:7], v[68:71], v[200:203], 0
	v_mfma_f32_16x16x32_bf16 v[0:3], v[76:79], v[200:203], 0
	v_mfma_f32_16x16x32_bf16 v[128:131], v[48:51], v[140:143], v[128:131]
	v_mfma_f32_16x16x32_bf16 v[64:67], v[60:63], v[140:143], v[64:67]
	v_mfma_f32_16x16x32_bf16 v[100:103], v[48:51], v[148:151], v[100:103]
	v_mfma_f32_16x16x32_bf16 v[88:91], v[60:63], v[148:151], v[88:91]
	v_mfma_f32_16x16x32_bf16 v[28:31], v[48:51], v[180:183], v[28:31]
	v_mfma_f32_16x16x32_bf16 v[24:27], v[60:63], v[180:183], v[24:27]
	v_mfma_f32_16x16x32_bf16 v[44:47], v[48:51], v[204:207], v[44:47]
	v_mfma_f32_16x16x32_bf16 v[48:51], v[56:59], v[200:203], 0
	v_mfma_f32_16x16x32_bf16 v[52:55], v[68:71], v[108:111], 0
	v_mfma_f32_16x16x32_bf16 v[32:35], v[84:87], v[140:143], v[32:35]
	v_mfma_f32_16x16x32_bf16 v[20:23], v[72:75], v[148:151], v[20:23]
	v_mfma_f32_16x16x32_bf16 v[16:19], v[84:87], v[148:151], v[16:19]
	v_mfma_f32_16x16x32_bf16 v[12:15], v[72:75], v[180:183], v[12:15]
	v_mfma_f32_16x16x32_bf16 v[8:11], v[84:87], v[180:183], v[8:11]
	v_mfma_f32_16x16x32_bf16 v[4:7], v[72:75], v[204:207], v[4:7]
	v_mfma_f32_16x16x32_bf16 v[0:3], v[84:87], v[204:207], v[0:3]
	v_mfma_f32_16x16x32_bf16 v[48:51], v[60:63], v[204:207], v[48:51]
	v_mfma_f32_16x16x32_bf16 v[56:59], v[72:75], v[140:143], v[52:55]
	s_setprio 0
	s_barrier
	s_add_i32 s77, 0, 0x18000
	s_add_i32 s76, 0, 0x1c000
	v_add_u32_e32 v72, s77, v220
	v_add_u32_e32 v80, s76, v220
	ds_read_b128 v[52:55], v72
	ds_read_b128 v[60:63], v72 offset:1024
	ds_read_b128 v[68:71], v72 offset:2048
	ds_read_b128 v[72:75], v72 offset:3072
	ds_read_b128 v[76:79], v80
	ds_read_b128 v[84:87], v80 offset:1024
	ds_read_b128 v[168:171], v80 offset:2048
	ds_read_b128 v[180:183], v80 offset:3072
	s_add_u32 s40, s72, 0x80000
	s_addc_u32 s41, s73, 0
	s_mov_b32 m0, s83
	v_lshl_add_u64 v[148:149], s[40:41], 0, v[184:185]
	ds_read_b128 v[80:83], v223 offset:32768
	ds_read_b128 v[108:111], v223 offset:33792
	ds_read_b128 v[140:143], v223 offset:34816
	ds_read_b128 v[144:147], v223 offset:35840
	ds_read_b128 v[176:179], v223 offset:36864
	ds_read_b128 v[200:203], v223 offset:37888
	ds_read_b128 v[204:207], v223 offset:38912
	ds_read_b128 v[208:211], v223 offset:39936
	global_load_lds_dwordx4 v[148:149], off
	v_lshl_add_u64 v[148:149], s[40:41], 0, v[188:189]
	s_mov_b32 m0, s84
	s_nop 0
	global_load_lds_dwordx4 v[148:149], off
	s_waitcnt vmcnt(8)
	s_waitcnt lgkmcnt(0)
	s_barrier
	s_setprio 1
	s_waitcnt lgkmcnt(0)
	v_mfma_f32_16x16x32_bf16 v[148:151], v[52:55], v[140:143], v[172:175]
	v_mfma_f32_16x16x32_bf16 v[172:175], v[60:63], v[144:147], v[148:151]
	v_mfma_f32_16x16x32_bf16 v[148:151], v[68:71], v[140:143], v[164:167]
	v_mfma_f32_16x16x32_bf16 v[164:167], v[72:75], v[144:147], v[148:151]
	v_mfma_f32_16x16x32_bf16 v[148:151], v[52:55], v[176:179], v[156:159]
	v_mfma_f32_16x16x32_bf16 v[40:43], v[52:55], v[80:83], v[40:43]
	v_mfma_f32_16x16x32_bf16 v[36:39], v[68:71], v[80:83], v[36:39]
	v_mfma_f32_16x16x32_bf16 v[156:159], v[60:63], v[200:203], v[148:151]
	v_mfma_f32_16x16x32_bf16 v[148:151], v[68:71], v[176:179], v[152:155]
	v_mfma_f32_16x16x32_bf16 v[104:107], v[76:79], v[80:83], v[104:107]
	v_mfma_f32_16x16x32_bf16 v[80:83], v[168:171], v[80:83], v[92:95]
	v_mfma_f32_16x16x32_bf16 v[40:43], v[60:63], v[108:111], v[40:43]
	v_mfma_f32_16x16x32_bf16 v[36:39], v[72:75], v[108:111], v[36:39]
	v_mfma_f32_16x16x32_bf16 v[152:155], v[72:75], v[200:203], v[148:151]
	v_mfma_f32_16x16x32_bf16 v[148:151], v[52:55], v[204:207], v[160:163]
	v_mfma_f32_16x16x32_bf16 v[104:107], v[84:87], v[108:111], v[104:107]
	v_mfma_f32_16x16x32_bf16 v[108:111], v[180:183], v[108:111], v[80:83]
	v_mfma_f32_16x16x32_bf16 v[80:83], v[76:79], v[140:143], v[96:99]
	v_mfma_f32_16x16x32_bf16 v[160:163], v[60:63], v[208:211], v[148:151]
	v_mfma_f32_16x16x32_bf16 v[148:151], v[84:87], v[144:147], v[80:83]
	v_mfma_f32_16x16x32_bf16 v[80:83], v[168:171], v[140:143], v[120:123]
	v_mfma_f32_16x16x32_bf16 v[144:147], v[180:183], v[144:147], v[80:83]
	v_mfma_f32_16x16x32_bf16 v[80:83], v[76:79], v[176:179], v[124:127]
	v_mfma_f32_16x16x32_bf16 v[140:143], v[84:87], v[200:203], v[80:83]
	v_mfma_f32_16x16x32_bf16 v[80:83], v[168:171], v[176:179], v[136:139]
	v_mfma_f32_16x16x32_bf16 v[136:139], v[180:183], v[200:203], v[80:83]
	v_mfma_f32_16x16x32_bf16 v[80:83], v[76:79], v[204:207], v[116:119]
	v_mfma_f32_16x16x32_bf16 v[132:135], v[68:71], v[204:207], v[132:135]
	v_mfma_f32_16x16x32_bf16 v[116:119], v[84:87], v[208:211], v[80:83]
	v_mfma_f32_16x16x32_bf16 v[80:83], v[168:171], v[204:207], v[112:115]
	v_mfma_f32_16x16x32_bf16 v[132:135], v[72:75], v[208:211], v[132:135]
	v_mfma_f32_16x16x32_bf16 v[112:115], v[180:183], v[208:211], v[80:83]
	s_setprio 0
	s_barrier
; #define PG8_STAGE(bufoff, gbase, voff) do { _Pragma("unroll") for (int _i = 0; _i < 2; ++_i) \
;         __builtin_amdgcn_global_load_lds((const unsigned*)((const char*)(gbase) + (voff)[_i]), (PG8_LAS unsigned*)(lds + (bufoff) + ldsw + _i * 8192), 16, 0, 0); } while (0)
; #define PG8_LDA(dst, b, h) do { _Pragma("unroll") for (int m = 0; m < 4; ++m) _Pragma("unroll") for (int k = 0; k < 2; ++k) dst[m][k] = *(const PG8_LAS bf16x8*)(lds + PG8_SA(b, h) + aoff + m * 2048 + k * 1024); } while (0)
; #define PG8_MMA(ai, bj, At, Bt) do { _Pragma("unroll") for (int m = 0; m < 4; ++m) _Pragma("unroll") for (int n = 0; n < 2; ++n) _Pragma("unroll") for (int k = 0; k < 2; ++k) \
;         acc[ai][bj][m][n] = __builtin_amdgcn_mfma_f32_16x16x32_bf16(Bt[n][k], At[m][k], acc[ai][bj][m][n], 0, 0, 0); } while (0)
; #define PG8_WAIT_V(n) asm volatile("s_waitcnt vmcnt(" #n ")" ::: "memory")
; #define PG8_WAIT_L(n) asm volatile("s_waitcnt lgkmcnt(" #n ")" ::: "memory")
; #define PG8_BAR __builtin_amdgcn_s_barrier()
; #define PG8_SCHED __builtin_amdgcn_sched_barrier(0)
; template <class Epi, class Sched, bool ALIGN_EPI = false, bool SP2 = false>
; __device__ __forceinline__ void gemm_phase(PG8_LAS unsigned char* lds, const Gemm g, const Sched& S, const Epi& E, const int wave_id_in) {
;     ...
;             PG8_LDA(At, 1, 1); PG8_STAGE(PG8_SB(1, 0), b3, voffB); PG8_STAGE(PG8_SB(1, 1), b3 + hstep, voffB); PG8_STAGE(PG8_SA(1, 0), a3, voffA);
;             PG8_WAIT_V(8); PG8_WAIT_L(0); PG8_BAR; __builtin_amdgcn_s_setprio(1); PG8_MMA(1, 0, At, B0); PG8_MMA(1, 1, At, B1); __builtin_amdgcn_s_setprio(0); PG8_BAR; PG8_SCHED;
	s_add_i32 s40, s77, s80
	s_nop 2
	v_lshl_add_u64 v[80:81], v[216:217], 0, s[34:35]
	s_mov_b32 m0, s40
	ds_read_b128 v[92:95], v223 offset:49152
	ds_read_b128 v[96:99], v223 offset:50176
	ds_read_b128 v[120:123], v223 offset:51200
	ds_read_b128 v[124:127], v223 offset:52224
	ds_read_b128 v[200:203], v223 offset:53248
	ds_read_b128 v[204:207], v223 offset:54272
	ds_read_b128 v[208:211], v223 offset:55296
	ds_read_b128 v[212:215], v223 offset:56320
	global_load_lds_dwordx4 v[80:81], off
	s_add_i32 m0, s40, 0x2000
	s_add_u32 s12, s12, 0x80080
	v_lshl_add_u64 v[80:81], v[218:219], 0, s[34:35]
	s_addc_u32 s13, s13, 0
	s_add_i32 s40, s76, s80
	global_load_lds_dwordx4 v[80:81], off
	v_lshl_add_u64 v[80:81], s[12:13], 0, v[186:187]
	s_mov_b32 m0, s40
	s_nop 0
	global_load_lds_dwordx4 v[80:81], off
	v_lshl_add_u64 v[80:81], s[12:13], 0, v[190:191]
	s_add_i32 m0, s40, 0x2000
	s_nop 0
	global_load_lds_dwordx4 v[80:81], off
	v_lshl_add_u64 v[80:81], v[226:227], 0, s[34:35]
	s_mov_b32 m0, s87
	s_nop 0
	global_load_lds_dwordx4 v[80:81], off
	v_lshl_add_u64 v[80:81], v[228:229], 0, s[34:35]
	s_mov_b32 m0, s88
	s_nop 0
	global_load_lds_dwordx4 v[80:81], off
	s_waitcnt vmcnt(8)
	s_waitcnt lgkmcnt(0)
	s_barrier
	s_setprio 1
	s_waitcnt lgkmcnt(0)
	v_mfma_f32_16x16x32_bf16 v[80:83], v[52:55], v[92:95], v[128:131]
	v_mfma_f32_16x16x32_bf16 v[44:47], v[52:55], v[208:211], v[44:47]
	v_mfma_f32_16x16x32_bf16 v[128:131], v[60:63], v[96:99], v[80:83]
	v_mfma_f32_16x16x32_bf16 v[80:83], v[52:55], v[120:123], v[100:103]
	v_mfma_f32_16x16x32_bf16 v[176:179], v[60:63], v[212:215], v[44:47]
	v_mfma_f32_16x16x32_bf16 v[44:47], v[68:71], v[208:211], v[48:51]
	v_mfma_f32_16x16x32_bf16 v[64:67], v[68:71], v[92:95], v[64:67]
	v_mfma_f32_16x16x32_bf16 v[100:103], v[60:63], v[124:127], v[80:83]
	v_mfma_f32_16x16x32_bf16 v[80:83], v[68:71], v[120:123], v[88:91]
	v_mfma_f32_16x16x32_bf16 v[28:31], v[52:55], v[200:203], v[28:31]
	v_mfma_f32_16x16x32_bf16 v[24:27], v[68:71], v[200:203], v[24:27]
	v_mfma_f32_16x16x32_bf16 v[52:55], v[72:75], v[212:215], v[44:47]
	v_mfma_f32_16x16x32_bf16 v[44:47], v[76:79], v[92:95], v[56:59]
	v_mfma_f32_16x16x32_bf16 v[32:35], v[168:171], v[92:95], v[32:35]
	v_mfma_f32_16x16x32_bf16 v[20:23], v[76:79], v[120:123], v[20:23]
	v_mfma_f32_16x16x32_bf16 v[16:19], v[168:171], v[120:123], v[16:19]
	v_mfma_f32_16x16x32_bf16 v[12:15], v[76:79], v[200:203], v[12:15]
	v_mfma_f32_16x16x32_bf16 v[8:11], v[168:171], v[200:203], v[8:11]
	v_mfma_f32_16x16x32_bf16 v[4:7], v[76:79], v[208:211], v[4:7]
	v_mfma_f32_16x16x32_bf16 v[0:3], v[168:171], v[208:211], v[0:3]
	v_mfma_f32_16x16x32_bf16 v[64:67], v[72:75], v[96:99], v[64:67]
	v_mfma_f32_16x16x32_bf16 v[88:91], v[72:75], v[124:127], v[80:83]
	v_mfma_f32_16x16x32_bf16 v[28:31], v[60:63], v[204:207], v[28:31]
	v_mfma_f32_16x16x32_bf16 v[24:27], v[72:75], v[204:207], v[24:27]
	v_mfma_f32_16x16x32_bf16 v[80:83], v[84:87], v[96:99], v[44:47]
	v_mfma_f32_16x16x32_bf16 v[32:35], v[180:183], v[96:99], v[32:35]
	v_mfma_f32_16x16x32_bf16 v[20:23], v[84:87], v[124:127], v[20:23]
	v_mfma_f32_16x16x32_bf16 v[16:19], v[180:183], v[124:127], v[16:19]
	v_mfma_f32_16x16x32_bf16 v[12:15], v[84:87], v[204:207], v[12:15]
	v_mfma_f32_16x16x32_bf16 v[8:11], v[180:183], v[204:207], v[8:11]
	v_mfma_f32_16x16x32_bf16 v[4:7], v[84:87], v[212:215], v[4:7]
	v_mfma_f32_16x16x32_bf16 v[0:3], v[180:183], v[212:215], v[0:3]
	s_setprio 0
	s_barrier
	s_add_i32 vcc_hi, vcc_hi, 2
	s_add_u32 s10, s10, 0x100
	s_addc_u32 s11, s11, 0
	s_add_u32 s75, s75, 0x100
	s_addc_u32 vcc_lo, vcc_lo, 0
	s_cmp_gt_u32 vcc_hi, 29
	s_cbranch_scc0 .LBB0_819
	s_branch .Lpeel_exit_ffnup

; #define PG8_BAR __builtin_amdgcn_s_barrier()
; template <class Epi, class Sched, bool ALIGN_EPI = false, bool SP2 = false>
; __device__ __forceinline__ void gemm_phase(PG8_LAS unsigned char* lds, const Gemm g, const Sched& S, const Epi& E, const int wave_id_in) {
;     ...
;         if constexpr (ALIGN_EPI) { if (wr == 0) PG8_BAR; }
.Lpeel_exit_ffnup:
	s_and_b64 vcc, exec, s[36:37]
	s_cbranch_vccz .LBB0_822
	s_barrier
